# phase 4: workgroups with (bid>>3)&1 run the SSD scan before the UQ/UKV GEMMs and conv (de-synchronised memory bursts), on v48
# speedup vs baseline: 1.0050x; 1.0050x over previous
; __global__ void __launch_bounds__(NTHR, 2) mk_fwd(Args a_by_value) {
;     ...
;             unsigned* subc = (unsigned*)(ws + WS_BAR) + XCD_BAR_WORDS + 64 * (layer * 8);
;             for (int item = bid; item < 256; item += G) { ssd_bc_slice(a, layer, item); sub_arrive(subc + 64 * (item >> 5)); }
;             for (int rep4 = 0; rep4 < REP_P4R; ++rep4) {
;             if (P4_EN(1)) {
;                 pg8::Gemm g{U + UQ, (const bf16_t*)(wsw + W_UQ), T, 768, 256, NU, 256}; pg8::StaticOrder S; S.init(T, 768, G, bid);
;                 EpiQ E{ws, (bf16_t*)(ws + WS_QR), (const float*)(ws + WS_CTL + CTL_QSS)};
;                 pg8::gemm_phase<EpiQ, pg8::StaticOrder, false>(lds, g, S, E);
;             }
;             if (P4_EN(2)) {
;                 pg8::Gemm g{U + UKV, (const bf16_t*)(wsw + W_UKV), T, 1024, 128, NU, 128}; pg8::StaticOrder S; S.init(T, 1024, G, bid);
;                 EpiKV E{ws, U, (const float*)(ws + WS_CTL + CTL_KVSS), a->mla_khn + layer * 96, (const float2*)(ws + WS_CS), (bf16_t*)(ws + WS_KF), (bf16_t*)(ws + WS_VT)};
;                 pg8::gemm_phase<EpiKV, pg8::StaticOrder, false>(lds, g, S, E);
;             }
;             if (P4_EN(3)) conv_mixer_rows(a, layer, G);
;             }
;             for (int item = bid; item < 256; item += G) { sub_wait(subc + 64 * (item >> 5), 32u); ssd_item(a, layer, item, lds); }
.LBB0_100:
	v_readlane_b32 s2, v255, 41
	s_nop 3
	s_cmp_eq_u32 s2, 1
	s_cbranch_scc0 .Lp4_gemm_entry
	v_writelane_b32 v255, s28, 20
	v_writelane_b32 v255, s29, 21
	s_branch .Lp4_ssd_entry

; __global__ void __launch_bounds__(NTHR, 2) mk_fwd(Args a_by_value) {
;     ...
;             for (int item = bid; item < 256; item += G) { sub_wait(subc + 64 * (item >> 5), 32u); ssd_item(a, layer, item, lds); }
.Lp4_tail:
	v_readlane_b32 s2, v255, 41
	s_nop 3
	s_cmp_lg_u32 s2, 1
	s_cbranch_scc1 .LBB0_209
	s_mov_b32 s2, 2
	s_nop 1
	v_writelane_b32 v255, s2, 41
	v_readlane_b32 s28, v255, 20
	v_readlane_b32 s29, v255, 21
	s_branch .Lp4_gemm_entry
